# scan: W and Q' A-fragments loaded straight from global (P5 writes both in MFMA fragment order, full-row stores), no LDS staging for them; KT written piece-major by P5 so its stores cover whole lines
# speedup vs baseline: 1.0259x; 1.0005x over previous
; #define LAS __attribute__((address_space(3)))
; __device__ __forceinline__ void prep_unit(const int PREP_STEPS, LAS unsigned char* lds, int uidx, bf16* Qg, bf16* Kg, bf16* Vg, bf16* KT, bf16* QK, const bf16* HALO, const float* wconv, const float* BETA, const float* GG, float* GC) {
;     const int tid = threadIdx.x, hb = tid >> 8, tl = tid & 255, lane = tid & 63, wq = (tid >> 6) & 3;
;     const int b = uidx >> 7, rem = uidx & 127, h = rem >> 4, cp = rem & 15, n = 2 * cp + hb;
;     const int gcid = b * 32 + n, m0 = b * 2048 + n * 64;
;     LAS unsigned char* L = lds + hb * PREP_HALF;
;     LAS bf16* Qs = (LAS bf16*)L; LAS bf16* Ks = Qs + 64 * 136; LAS bf16* Vs = Ks + 64 * 136;
;     LAS float* Af = (LAS float*)(L + 3 * 17408); LAS float* gcs = Af + 64 * 68; LAS float* betas = gcs + 64; LAS float* egcs = betas + 64;
;     if (PREP_STEPS & 1) {
;     ...
;         { const int dk = tl & 127, rh = tl >> 7; bf16* dst = KT + ((size_t)(gcid * 8 + h) * 128 + dk) * 64 + 32 * rh;
; #pragma unroll
.LBB0_634:
	s_cmp_lt_i32 s64, 6
	s_cselect_b64 s[0:1], -1, 0
	s_and_b64 s[0:1], s[0:1], s[6:7]
	s_andn2_b64 vcc, exec, s[0:1]
	s_cbranch_vccnz .LBB0_774
	s_cmpk_gt_i32 s2, 0x3ff
	v_writelane_b32 v244, s0, 0
	s_nop 1
	v_writelane_b32 v244, s1, 1
	v_writelane_b32 v244, s95, 2
	v_writelane_b32 v244, s80, 3
	s_nop 1
	v_writelane_b32 v244, s81, 4
	v_writelane_b32 v244, s94, 5
	s_nop 1
	v_writelane_b32 v244, s95, 6
	s_cbranch_scc1 .LBB0_768
	v_lshlrev_b32_e32 v0, 3, v154
	v_lshrrev_b32_e32 v57, 8, v154
	s_mov_b32 s0, 0x11300
	v_and_b32_e32 v113, 0x78, v0
	v_mov_b32_e32 v0, 64
	v_mad_u32_u24 v110, v57, s0, 0
	v_cmp_lt_u32_sdwa s[0:1], v154, v0 src0_sel:BYTE_0 src1_sel:DWORD
	s_load_dwordx4 s[4:7], s[56:57], 0x110
	v_lshrrev_b32_e32 v4, 2, v154
	v_writelane_b32 v244, s0, 7
	v_and_b32_e32 v6, 48, v152
	v_and_b32_e32 v114, 60, v4
	v_writelane_b32 v244, s1, 8
	v_cmp_eq_u32_e64 s[0:1], 0, v152
	v_and_b32_e32 v2, 32, v4
	v_and_b32_e32 v4, 48, v4
	v_writelane_b32 v244, s0, 9
	v_add_u32_e32 v125, v110, v6
	v_lshrrev_b32_e32 v6, 2, v152
	v_writelane_b32 v244, s1, 10
	v_cmp_gt_u32_e64 s[0:1], 2, v152
	v_and_or_b32 v12, v6, 12, v4
	v_and_b32_e32 v56, 0x7f, v154
	v_writelane_b32 v244, s0, 11
	v_or_b32_e32 v14, 1, v12
	s_waitcnt lgkmcnt(0)
	s_bitcmp1_b32 s6, 0
	v_writelane_b32 v244, s1, 12
	v_cmp_gt_u32_e64 s[0:1], 4, v152
	v_subrev_co_u32_e32 v116, vcc, 1, v114
	s_nop 0
	v_writelane_b32 v244, s0, 13
	v_mul_u32_u24_e32 v5, 0x110, v2
	v_lshlrev_b32_e32 v7, 1, v56
	v_writelane_b32 v244, s1, 14
	v_cmp_gt_u32_e64 s[0:1], 8, v152
	s_cselect_b64 s[92:93], -1, 0
	s_xor_b64 s[94:95], vcc, -1
	v_writelane_b32 v244, s0, 15
	v_add3_u32 v124, v110, v5, v7
	v_or_b32_e32 v5, v4, v156
	v_writelane_b32 v244, s1, 16
	v_cmp_gt_u32_e64 s[0:1], 16, v152
	v_or_b32_e32 v15, 2, v12
	s_movk_i32 s3, 0x100
	v_writelane_b32 v244, s0, 17
	v_mov_b32_e32 v0, 2
	s_bitcmp1_b32 s6, 1
	v_writelane_b32 v244, s1, 18
	v_cmp_gt_u32_e64 s[0:1], 32, v152
	v_mul_u32_u24_e32 v5, 0x88, v5
	v_or_b32_e32 v16, 3, v12
	v_writelane_b32 v244, s0, 19
	v_cmp_gt_u32_e32 vcc, s3, v154
	s_movk_i32 s3, 0x80
	v_writelane_b32 v244, s1, 20
	v_cmp_gt_u32_e64 s[0:1], v12, v156
	v_mul_u32_u24_e32 v1, 0x11300, v57
	v_add_u32_e32 v3, 0x11000, v110
	v_writelane_b32 v244, s0, 21
	v_add_u32_e32 v111, 0x11100, v110
	v_add_u32_e32 v112, 0x11200, v110
	v_writelane_b32 v244, s1, 22
	v_cmp_ge_u32_e64 s[0:1], v14, v156
	v_lshlrev_b32_sdwa v0, v0, v154 dst_sel:DWORD dst_unused:UNUSED_PAD src0_sel:DWORD src1_sel:BYTE_0
	s_cselect_b64 s[84:85], -1, 0
	v_writelane_b32 v244, s0, 23
	v_lshl_add_u32 v126, v5, 1, v125
	v_or_b32_e32 v5, 16, v156
	v_writelane_b32 v244, s1, 24
	v_cmp_ge_u32_e64 s[0:1], v15, v156
	v_or_b32_e32 v9, 32, v156
	v_or_b32_e32 v11, 48, v156
	v_lshlrev_b32_e32 v13, 2, v156
	v_lshlrev_b32_e32 v4, 2, v12
	v_lshlrev_b32_e32 v6, 2, v14
	v_writelane_b32 v244, s0, 25
	v_lshlrev_b32_e32 v8, 2, v15
	v_lshlrev_b32_e32 v10, 2, v16
	s_bitcmp1_b32 s6, 2
	v_cmp_lt_u32_sdwa s[4:5], v154, s3 src0_sel:BYTE_0 src1_sel:DWORD
	v_add_u32_e32 v121, v3, v0
	v_add_u32_e32 v122, v111, v0
	v_add_u32_e32 v123, v112, v0
	v_lshlrev_b32_e32 v0, 6, v56
	v_mul_u32_u24_e32 v127, 0x110, v156
	v_add_u32_e32 v128, v3, v13
	v_add_u32_e32 v129, v3, v4
	v_add_u32_e32 v132, v3, v6
	v_writelane_b32 v244, s1, 26
	v_add_u32_e32 v134, v3, v8
	v_add_u32_e32 v136, v3, v10
	v_lshl_add_u32 v138, v5, 2, v3
	v_lshl_add_u32 v140, v9, 2, v3
	v_lshl_add_u32 v142, v11, 2, v3
	s_cselect_b64 s[0:1], -1, 0
	s_xor_b64 s[4:5], vcc, s[4:5]
	v_or_b32_e32 v3, v1, v13
	v_or_b32_e32 v1, v1, v7
	v_mov_b32_e32 v55, 0
	v_add_u32_e32 v130, v111, v4
	v_add3_u32 v131, v110, v127, v4
	v_lshl_or_b32 v4, v12, 6, v156
	v_add_u32_e32 v133, v111, v6
	v_lshl_or_b32 v6, v14, 6, v156
	v_add_u32_e32 v135, v111, v8
	v_lshl_or_b32 v8, v15, 6, v156
	v_add_u32_e32 v137, v111, v10
	v_lshl_or_b32 v10, v16, 6, v156
	s_xor_b64 s[4:5], s[4:5], -1
	v_add_u32_e32 v3, 0, v3
	v_add_u32_e32 v1, 0, v1
	v_lshrrev_b32_e32 v58, 2, v0
	v_mbcnt_lo_u32_b32 v0, -1, 0
	s_mov_b32 s83, 0
	v_add_u32_e32 v115, -3, v114
	v_add_u32_e32 v117, -2, v114
	v_or_b32_e32 v50, 1, v114
	v_or_b32_e32 v52, 2, v114
	v_or_b32_e32 v118, 3, v114
	v_lshl_add_u32 v119, v113, 1, v110
	v_mul_u32_u24_e32 v120, 0x110, v114
	v_mov_b32_e32 v51, v55
	v_mov_b32_e32 v53, v55
	v_cmp_ge_u32_e64 s[18:19], v12, v156
	v_cmp_gt_u32_e64 s[26:27], v15, v156
	v_cmp_ge_u32_e64 s[28:29], v16, v156
	v_cmp_gt_u32_e64 s[30:31], v16, v156
	v_cmp_ge_u32_e64 s[34:35], v12, v5
	v_cmp_gt_u32_e64 s[36:37], v12, v5
	v_add_u32_e32 v139, 0x1100, v131
	v_cmp_ge_u32_e64 s[38:39], v14, v5
	v_cmp_ge_u32_e64 s[40:41], v15, v5
	v_cmp_gt_u32_e64 s[42:43], v15, v5
	v_cmp_ge_u32_e64 s[44:45], v16, v5
	v_cmp_gt_u32_e64 s[46:47], v16, v5
	v_cmp_ge_u32_e64 s[48:49], v12, v9
	v_cmp_gt_u32_e64 s[50:51], v12, v9
	v_add_u32_e32 v141, 0x2200, v131
	v_cmp_ge_u32_e64 s[52:53], v14, v9
	v_cmp_ge_u32_e64 s[20:21], v15, v9
	v_cmp_gt_u32_e64 s[22:23], v15, v9
	v_cmp_ge_u32_e64 s[58:59], v16, v9
	v_cmp_gt_u32_e64 s[60:61], v16, v9
	v_cmp_ge_u32_e64 s[62:63], v12, v11
	v_cmp_gt_u32_e64 s[64:65], v12, v11
	v_add_u32_e32 v143, 0x3300, v131
	v_cmp_ge_u32_e64 s[66:67], v14, v11
	v_cmp_ge_u32_e64 s[68:69], v15, v11
	v_add_u32_e32 v144, v110, v13
	s_and_b64 s[4:5], s[0:1], s[4:5]
	v_add_u32_e32 v145, 0xcc00, v3
	v_add_u32_e32 v146, 0x4400, v1
	s_movk_i32 s79, 0x1800
	v_lshlrev_b32_e32 v60, 8, v2
	v_add_u32_e32 v60, 0x1000, v60
	v_lshlrev_b32_e32 v62, 1, v4
	v_lshlrev_b32_e32 v64, 1, v6
	v_lshlrev_b32_e32 v66, 1, v8
	v_lshlrev_b32_e32 v68, 1, v10
	v_mbcnt_hi_u32_b32 v147, -1, v0
	s_mov_b32 s3, s2
	v_cmp_gt_u32_e64 s[70:71], v15, v11
	v_cmp_ge_u32_e64 s[72:73], v16, v11
	v_cmp_gt_u32_e64 s[74:75], v16, v11
	s_branch .LBB0_638
; __device__ __forceinline__ unsigned short f2bf(float f) { return (unsigned short)(cvt_pk_bf16(f, 0.f) & 0xffffu); }
; __device__ __forceinline__ void prep_unit(const int PREP_STEPS, LAS unsigned char* lds, int uidx, bf16* Qg, bf16* Kg, bf16* Vg, bf16* KT, bf16* QK, const bf16* HALO, const float* wconv, const float* BETA, const float* GG, float* GC) {
;     ...
;             for (int r = 0; r < 16; ++r) { const unsigned short ub = f2bf(au[r]), wb = f2bf(aw[r]); Vs[(16 * I + r) * 136 + c] = ub; Ks[(16 * I + r) * 136 + c] = wb;
;                 dstu[(size_t)(16 * I + r) * D] = ub; dstw[(size_t)(16 * I + r) * D] = wb; }
.LBB0_637:
	s_or_b64 exec, exec, s[6:7]
	s_waitcnt lgkmcnt(0)
	s_barrier
	v_and_b32_e32 v32, 0xff, v154
	v_lshrrev_b32_e32 v33, 4, v32
	v_and_b32_e32 v34, 15, v32
	v_lshlrev_b32_e32 v34, 4, v34
	v_mul_u32_u24_e32 v35, 0x110, v33
	v_add3_u32 v35, v35, v34, v110
	v_add_u32_e32 v36, v70, v33
	v_lshl_add_u32 v36, v36, 11, v34
	v_add_u32_e32 v37, 0x8000, v36
	v_add_u32_e32 v38, 0x10000, v36
	v_add_u32_e32 v39, 0x18000, v36
	v_and_b32_e32 v40, 15, v32
	v_mul_u32_u24_e32 v40, 0x110, v40
	v_lshl_add_u32 v40, v33, 4, v40
	v_add_u32_e32 v40, v40, v110
	s_lshl_b32 s0, s82, 8
	s_add_u32 s12, s10, s0
	s_addc_u32 s13, s11, 0
	s_add_u32 s14, s8, s0
	s_addc_u32 s15, s9, 0
	ds_read_b128 v[0:3], v35 offset:34816
	ds_read_b128 v[4:7], v35 offset:39168
	ds_read_b128 v[8:11], v35 offset:43520
	ds_read_b128 v[12:15], v35 offset:47872
	ds_read_b128 v[16:19], v40 offset:17408
	ds_read_b128 v[20:23], v40 offset:21760
	ds_read_b128 v[24:27], v40 offset:26112
	ds_read_b128 v[28:31], v40 offset:30464
	s_waitcnt lgkmcnt(0)
	s_barrier
	global_store_dwordx4 v36, v[0:3], s[12:13]
	global_store_dwordx4 v37, v[4:7], s[12:13]
	global_store_dwordx4 v38, v[8:11], s[12:13]
	global_store_dwordx4 v39, v[12:15], s[12:13]
	global_store_dwordx4 v36, v[16:19], s[14:15]
	global_store_dwordx4 v37, v[20:23], s[14:15]
	global_store_dwordx4 v38, v[24:27], s[14:15]
	global_store_dwordx4 v39, v[28:31], s[14:15]
	s_add_i32 s3, s3, s88
	s_cmpk_gt_i32 s3, 0x3ff
	s_cbranch_scc1 .LBB0_768

; #define LAS __attribute__((address_space(3)))
; __device__ __forceinline__ void prep_unit(const int PREP_STEPS, LAS unsigned char* lds, int uidx, bf16* Qg, bf16* Kg, bf16* Vg, bf16* KT, bf16* QK, const bf16* HALO, const float* wconv, const float* BETA, const float* GG, float* GC) {
;     ...
;     if (PREP_STEPS & 2) {
;         const int c8 = tl & 15, rg = tl >> 4, colh = h * 128 + 8 * c8;
; #pragma unroll
;         for (int r = 0; r < 4; ++r) *(u32x4*)(Qg + (size_t)(m0 + 4 * rg + r) * D + colh) = *(const LAS u32x4*)(Qs + (4 * rg + r) * 136 + 8 * c8);
;         { const int dk = tl & 127, rh = tl >> 7; bf16* dst = KT + ((size_t)(gcid * 8 + h) * 128 + dk) * 64 + 32 * rh;
; #pragma unroll
;             for (int q4 = 0; q4 < 4; ++q4) { u32x4 w; unsigned t0[4];
; #pragma unroll
;                 for (int e = 0; e < 4; ++e) { const int i = 32 * rh + 8 * q4 + 2 * e; t0[e] = (unsigned)Ks[i * 136 + dk] | ((unsigned)Ks[(i + 1) * 136 + dk] << 16); }
;                 w.x = t0[0]; w.y = t0[1]; w.z = t0[2]; w.w = t0[3]; *(u32x4*)(dst + 8 * q4) = w; } }
;         const int ti = wq, li = lane & 15, lq = lane >> 4;
;         f32x4 accA[4], accQ[4];
; #pragma unroll
;         for (int tj = 0; tj < 4; ++tj) { accA[tj] = (f32x4){0.f, 0.f, 0.f, 0.f}; accQ[tj] = (f32x4){0.f, 0.f, 0.f, 0.f}; }
; #pragma unroll
;         for (int ks = 0; ks < 4; ++ks) {
;             const bf16x8 aK = *(const LAS bf16x8*)(Ks + (16 * ti + li) * 136 + 32 * ks + 8 * lq), aQ = *(const LAS bf16x8*)(Qs + (16 * ti + li) * 136 + 32 * ks + 8 * lq);
; #pragma unroll
;             for (int tj = 0; tj < 4; ++tj) { const bf16x8 bK = *(const LAS bf16x8*)(Ks + (16 * tj + li) * 136 + 32 * ks + 8 * lq);
;                 accA[tj] = __builtin_amdgcn_mfma_f32_16x16x32_bf16(aK, bK, accA[tj], 0, 0, 0); accQ[tj] = __builtin_amdgcn_mfma_f32_16x16x32_bf16(aQ, bK, accQ[tj], 0, 0, 0); }
;         }
.LBB0_696:
	s_waitcnt lgkmcnt(0)
	s_barrier
	s_andn2_b64 vcc, exec, s[84:85]
	s_cbranch_vccnz .LBB0_762
	ds_read_b128 v[0:3], v126 offset:17408
	v_add_u32_e32 v63, v125, v127
	ds_read_b128 v[4:7], v63 offset:17408
	ds_read_b128 v[8:11], v126 offset:17472
	ds_read_b128 v[12:15], v63 offset:17472
	ds_read_b128 v[20:23], v126
	s_waitcnt vmcnt(0)
	ds_read_b128 v[24:27], v126 offset:64
	ds_read_b128 v[28:31], v63 offset:21760
	ds_read_b128 v[32:35], v63 offset:21824
	ds_read_b128 v[40:43], v63 offset:26112
	ds_read_b128 v[44:47], v63 offset:26176
	ds_read_b128 v[76:79], v63 offset:30464
	ds_read_b128 v[80:83], v63 offset:30528
	v_or_b32_e32 v48, v70, v114
	s_waitcnt lgkmcnt(0)
	v_mfma_f32_16x16x32_bf16 v[16:19], v[0:3], v[4:7], 0
	v_lshlrev_b32_e32 v49, 1, v113
	v_lshl_or_b32 v54, s82, 8, v49
	v_ashrrev_i32_e32 v49, 31, v48
	v_mfma_f32_16x16x32_bf16 v[4:7], v[20:23], v[4:7], 0
	v_lshl_add_u64 v[88:89], s[16:17], 0, v[54:55]
	v_lshrrev_b32_e32 v54, 3, v113
	v_and_or_b32 v54, v114, 48, v54
	v_and_b32_e32 v84, 12, v114
	v_mul_u32_u24_e32 v54, 0x110, v54
	v_lshl_add_u32 v54, v84, 4, v54
	v_add_u32_e32 v54, v110, v54
	v_lshlrev_b64 v[84:85], 11, v[48:49]
	v_mfma_f32_16x16x32_bf16 v[36:39], v[0:3], v[28:31], 0
	v_lshl_add_u64 v[90:91], v[88:89], 0, v[84:85]
	ds_read_b128 v[84:87], v54 offset:16
	v_mov_b32_e32 v61, v55
	v_mfma_f32_16x16x32_bf16 v[28:31], v[20:23], v[28:31], 0
	s_mov_b64 s[0:1], 0xad30000
	v_mfma_f32_16x16x32_bf16 v[72:75], v[0:3], v[40:43], 0
	v_mfma_f32_16x16x32_bf16 v[40:43], v[20:23], v[40:43], 0
	v_mfma_f32_16x16x32_bf16 v[0:3], v[0:3], v[76:79], 0
	v_mfma_f32_16x16x32_bf16 v[20:23], v[20:23], v[76:79], 0
	ds_read_b128 v[76:79], v54
	s_waitcnt lgkmcnt(0)
	global_store_dwordx4 v[90:91], v[76:79], off
	v_mfma_f32_16x16x32_bf16 v[16:19], v[8:11], v[12:15], v[16:19]
	v_mfma_f32_16x16x32_bf16 v[4:7], v[24:27], v[12:15], v[4:7]
	v_or_b32_e32 v12, 1, v48
	v_ashrrev_i32_e32 v13, 31, v12
	v_lshlrev_b64 v[12:13], 11, v[12:13]
	v_lshl_add_u64 v[12:13], v[88:89], 0, v[12:13]
	global_store_dwordx4 v[12:13], v[84:87], off
	ds_read_b128 v[12:15], v54 offset:32
	v_mfma_f32_16x16x32_bf16 v[36:39], v[8:11], v[32:35], v[36:39]
	v_mfma_f32_16x16x32_bf16 v[28:31], v[24:27], v[32:35], v[28:31]
	v_or_b32_e32 v32, 2, v48
	v_ashrrev_i32_e32 v33, 31, v32
	v_lshlrev_b64 v[32:33], 11, v[32:33]
	v_lshl_add_u64 v[76:77], v[88:89], 0, v[32:33]
	ds_read_b128 v[32:35], v54 offset:48
	v_mfma_f32_16x16x32_bf16 v[72:75], v[8:11], v[44:47], v[72:75]
	s_waitcnt lgkmcnt(1)
	global_store_dwordx4 v[76:77], v[12:15], off
	v_mfma_f32_16x16x32_bf16 v[40:43], v[24:27], v[44:47], v[40:43]
	s_nop 0
	v_or_b32_e32 v12, 3, v48
	ds_read_b128 v[44:47], v126 offset:17536
	v_ashrrev_i32_e32 v13, 31, v12
	v_mfma_f32_16x16x32_bf16 v[8:11], v[8:11], v[80:83], v[0:3]
	ds_read_b128 v[76:79], v126 offset:128
	ds_read_b128 v[84:87], v63 offset:17536
	s_nop 0
	v_lshlrev_b64 v[0:1], 11, v[12:13]
	v_lshl_add_u64 v[12:13], v[88:89], 0, v[0:1]
	v_mfma_f32_16x16x32_bf16 v[20:23], v[24:27], v[80:83], v[20:23]
	ds_read_b128 v[0:3], v126 offset:17600
	ds_read_b128 v[24:27], v63 offset:17600
	s_waitcnt lgkmcnt(5)
	global_store_dwordx4 v[12:13], v[32:35], off
	ds_read_b128 v[80:83], v63 offset:21888
	ds_read_b128 v[12:15], v126 offset:192
	v_lshl_or_b32 v32, v59, 3, s82
	v_ashrrev_i32_e32 v33, 31, v32
	s_waitcnt lgkmcnt(1)
	v_mfma_f32_16x16x32_bf16 v[34:37], v[44:47], v[80:83], v[36:39]
	v_mov_b32_e32 v59, v55
	ds_read_b128 v[88:91], v63 offset:26240
	s_nop 0
	v_lshlrev_b64 v[38:39], 14, v[32:33]
	v_lshl_add_u64 v[38:39], s[14:15], 0, v[38:39]
	v_mfma_f32_16x16x32_bf16 v[80:83], v[76:79], v[80:83], v[28:31]
	ds_read_b128 v[92:95], v63 offset:26304
	s_nop 1
	v_lshl_add_u64 v[28:29], v[38:39], 0, v[58:59]
	v_mfma_f32_16x16x32_bf16 v[16:19], v[44:47], v[84:87], v[16:19]
	v_lshl_add_u64 v[96:97], v[28:29], 0, v[60:61]
	ds_read_b128 v[28:31], v63 offset:30592
	v_lshl_add_u64 v[98:99], v[96:97], 0, s[0:1]
	v_mfma_f32_16x16x32_bf16 v[4:7], v[76:79], v[84:87], v[4:7]
	ds_read_b128 v[84:87], v63 offset:21952
	s_mov_b32 s0, 0xad30000
	s_waitcnt lgkmcnt(3)
; #define LAS __attribute__((address_space(3)))
; __device__ __forceinline__ void prep_unit(const int PREP_STEPS, LAS unsigned char* lds, int uidx, bf16* Qg, bf16* Kg, bf16* Vg, bf16* KT, bf16* QK, const bf16* HALO, const float* wconv, const float* BETA, const float* GG, float* GC) {
;     ...
;         { const int dk = tl & 127, rh = tl >> 7; bf16* dst = KT + ((size_t)(gcid * 8 + h) * 128 + dk) * 64 + 32 * rh;
; #pragma unroll
;             for (int q4 = 0; q4 < 4; ++q4) { u32x4 w; unsigned t0[4];
; #pragma unroll
;                 for (int e = 0; e < 4; ++e) { const int i = 32 * rh + 8 * q4 + 2 * e; t0[e] = (unsigned)Ks[i * 136 + dk] | ((unsigned)Ks[(i + 1) * 136 + dk] << 16); }
;                 w.x = t0[0]; w.y = t0[1]; w.z = t0[2]; w.w = t0[3]; *(u32x4*)(dst + 8 * q4) = w; } }
;         const int ti = wq, li = lane & 15, lq = lane >> 4;
;         f32x4 accA[4], accQ[4];
; #pragma unroll
;         for (int tj = 0; tj < 4; ++tj) { accA[tj] = (f32x4){0.f, 0.f, 0.f, 0.f}; accQ[tj] = (f32x4){0.f, 0.f, 0.f, 0.f}; }
; #pragma unroll
;         for (int ks = 0; ks < 4; ++ks) {
;             const bf16x8 aK = *(const LAS bf16x8*)(Ks + (16 * ti + li) * 136 + 32 * ks + 8 * lq), aQ = *(const LAS bf16x8*)(Qs + (16 * ti + li) * 136 + 32 * ks + 8 * lq);
; #pragma unroll
;             for (int tj = 0; tj < 4; ++tj) { const bf16x8 bK = *(const LAS bf16x8*)(Ks + (16 * tj + li) * 136 + 32 * ks + 8 * lq);
;                 accA[tj] = __builtin_amdgcn_mfma_f32_16x16x32_bf16(aK, bK, accA[tj], 0, 0, 0); accQ[tj] = __builtin_amdgcn_mfma_f32_16x16x32_bf16(aQ, bK, accQ[tj], 0, 0, 0); }
;         }
;         bf16* qkg = QK + (size_t)(gcid * 8 + h) * 4096;
; #pragma unroll
;         for (int tj = 0; tj < 4; ++tj)
; #pragma unroll
;             for (int r = 0; r < 4; ++r) { const int i = 16 * ti + 4 * lq + r, j = 16 * tj + li;
	v_mfma_f32_16x16x32_bf16 v[72:75], v[44:47], v[88:91], v[72:75]
	v_mfma_f32_16x16x32_bf16 v[38:41], v[76:79], v[88:91], v[40:43]
	ds_read_b128 v[88:91], v63 offset:30656
	s_waitcnt lgkmcnt(2)
	v_mfma_f32_16x16x32_bf16 v[42:45], v[44:47], v[28:31], v[8:11]
	s_nop 2
	ds_read_u16 v8, v124 offset:17408
	ds_read_u16 v9, v124 offset:17680
	ds_read_u16 v10, v124 offset:17952
	ds_read_u16 v11, v124 offset:18224
	ds_read_u16 v54, v124 offset:18496
	ds_read_u16 v59, v124 offset:18768
	ds_read_u16 v61, v124 offset:19040
	ds_read_u16 v63, v124 offset:19312
	s_waitcnt lgkmcnt(6)
	v_lshl_or_b32 v8, v9, 16, v8
	s_waitcnt lgkmcnt(4)
	v_lshl_or_b32 v9, v11, 16, v10
	v_mfma_f32_16x16x32_bf16 v[46:49], v[76:79], v[28:31], v[20:23]
	s_waitcnt lgkmcnt(2)
	v_lshl_or_b32 v10, v59, 16, v54
	s_waitcnt lgkmcnt(0)
	v_lshl_or_b32 v11, v63, 16, v61
	v_mfma_f32_16x16x32_bf16 v[28:31], v[0:3], v[24:27], v[16:19]
	s_nop 2
	v_add_co_u32_e32 v16, vcc, s0, v96
	v_mfma_f32_16x16x32_bf16 v[24:27], v[12:15], v[24:27], v[4:7]
	s_nop 0
	v_addc_co_u32_e32 v17, vcc, 0, v97, vcc
	global_store_dwordx4 v[16:17], v[8:11], off offset:-4096
	ds_read_u16 v4, v124 offset:19584
	ds_read_u16 v5, v124 offset:19856
	ds_read_u16 v6, v124 offset:20128
	ds_read_u16 v7, v124 offset:20400
	ds_read_u16 v8, v124 offset:20672
	ds_read_u16 v9, v124 offset:20944
	ds_read_u16 v10, v124 offset:21216
	ds_read_u16 v11, v124 offset:21488
	s_waitcnt lgkmcnt(6)
	v_lshl_or_b32 v4, v5, 16, v4
	s_waitcnt lgkmcnt(4)
	v_lshl_or_b32 v5, v7, 16, v6
	s_waitcnt lgkmcnt(2)
	v_lshl_or_b32 v6, v9, 16, v8
	v_mfma_f32_16x16x32_bf16 v[20:23], v[0:3], v[84:87], v[34:37]
	s_waitcnt lgkmcnt(0)
	v_lshl_or_b32 v7, v11, 16, v10
	global_store_dwordx4 v[98:99], v[4:7], off offset:-2048
	ds_read_u16 v4, v124 offset:21760
	ds_read_u16 v5, v124 offset:22032
	ds_read_u16 v6, v124 offset:22304
	ds_read_u16 v7, v124 offset:22576
	ds_read_u16 v34, v124 offset:22848
	ds_read_u16 v35, v124 offset:23120
	ds_read_u16 v36, v124 offset:23392
	ds_read_u16 v37, v124 offset:23664
	s_waitcnt lgkmcnt(6)
	v_lshl_or_b32 v4, v5, 16, v4
	s_waitcnt lgkmcnt(4)
	v_lshl_or_b32 v5, v7, 16, v6
	s_waitcnt lgkmcnt(2)
	v_lshl_or_b32 v6, v35, 16, v34
	v_mfma_f32_16x16x32_bf16 v[16:19], v[12:15], v[84:87], v[80:83]
	s_waitcnt lgkmcnt(0)
	v_lshl_or_b32 v7, v37, 16, v36
	global_store_dwordx4 v[98:99], v[4:7], off
	v_mfma_f32_16x16x32_bf16 v[8:11], v[0:3], v[92:95], v[72:75]
	s_nop 0
	v_mfma_f32_16x16x32_bf16 v[4:7], v[12:15], v[92:95], v[38:41]
	ds_read_u16 v34, v124 offset:23936
	ds_read_u16 v35, v124 offset:24208
	ds_read_u16 v36, v124 offset:24480
	ds_read_u16 v37, v124 offset:24752
	ds_read_u16 v38, v124 offset:25024
	ds_read_u16 v39, v124 offset:25296
	ds_read_u16 v40, v124 offset:25568
	ds_read_u16 v41, v124 offset:25840
	s_waitcnt lgkmcnt(6)
	v_lshl_or_b32 v34, v35, 16, v34
	s_waitcnt lgkmcnt(4)
	v_lshl_or_b32 v35, v37, 16, v36
	v_mfma_f32_16x16x32_bf16 v[0:3], v[0:3], v[88:91], v[42:45]
	s_waitcnt lgkmcnt(2)
	v_lshl_or_b32 v36, v39, 16, v38
	s_waitcnt lgkmcnt(0)
	v_lshl_or_b32 v37, v41, 16, v40
	global_store_dwordx4 v[98:99], v[34:37], off offset:2048
	v_mfma_f32_16x16x32_bf16 v[12:15], v[12:15], v[88:91], v[46:49]
	s_nop 0
	v_mov_b32_e32 v34, 0
	v_mov_b32_e32 v35, 0
	s_and_saveexec_b64 s[0:1], s[18:19]
	s_cbranch_execz .LBB0_699
	ds_read_b32 v35, v129
	ds_read_b32 v36, v128
	s_waitcnt lgkmcnt(0)
	v_sub_f32_e32 v35, v35, v36
	v_mul_f32_e32 v35, 0x3fb8aa3b, v35
	v_exp_f32_e32 v35, v35

; #define LAS __attribute__((address_space(3)))
; __device__ __forceinline__ float bf2f(unsigned short b) { return __uint_as_float((unsigned)b << 16); }
; __device__ __forceinline__ void scan_load(ScanFrag& f, int n, int b, int h, int ti, int s, int li, int lq, int ucol, const bf16* Qg, const bf16* Kg, const bf16* Vg, const bf16* KT, const bf16* QK, const float* GC) {
;     const int gcid = b * 32 + n, m0 = b * 2048 + n * 64;
;     const bf16* wrow = Kg + (size_t)(m0 + 16 * ti + li) * D + h * 128 + 8 * lq; const bf16* qrow = Qg + (size_t)(m0 + 16 * ti + li) * D + h * 128 + 8 * lq;
; #pragma unroll
;     for (int ks = 0; ks < 4; ++ks) { f.wA[ks] = *(const bf16x8*)(wrow + 32 * ks); f.qA[ks] = *(const bf16x8*)(qrow + 32 * ks); }
;     const bf16* qkrow = QK + ((size_t)(gcid * 8 + h) * 64 + 16 * ti + li) * 64 + 8 * lq; const bf16* ktrow = KT + ((size_t)(gcid * 8 + h) * 128 + 16 * s + li) * 64 + 8 * lq;
; #pragma unroll
;     for (int k2 = 0; k2 < 2; ++k2) { f.qkA[k2] = *(const bf16x8*)(qkrow + 32 * k2); f.kA[k2] = *(const bf16x8*)(ktrow + 32 * k2); }
;     const int rowb = m0 + 16 * ti + 4 * lq;
; #pragma unroll
;     for (int r = 0; r < 4; ++r) { f.uval[r] = bf2f(Vg[(size_t)(rowb + r) * D + ucol]); f.gcr[r] = GC[(size_t)(rowb + r) * 8 + h]; }
;     f.gl = GC[(size_t)(m0 + 63) * 8 + h];
; }
; __device__ __forceinline__ void scan_unit(LAS unsigned char* lds, int uidx, const bf16* Qg, const bf16* Kg, bf16* Vg, const bf16* KT, const bf16* QK, const float* GC, float* SSQ, float* sp_gdn) {
;     const int tid = threadIdx.x, lane = tid & 63, s = __builtin_amdgcn_readfirstlane(tid >> 6);
;     const int xc = uidx & 7, yy = uidx >> 3, slab = yy & 3, bh = xc * 8 + (yy >> 2), b = bh >> 3, h = bh & 7;
;     LAS bf16* St = (LAS bf16*)lds; LAS bf16* Vt = St + 2 * 32 * 136; LAS bf16* Vts = Vt + 32 * 72;
;     const int ti = s >> 1, c = s & 1, li = lane & 15, lq = lane >> 4;
;     f32x4 S0 = (f32x4){0.f, 0.f, 0.f, 0.f}, S1 = S0;
;     const int ucol = h * 128 + slab * 32 + 16 * c + li;
;     ScanFrag cur, nxt;
;     scan_load(cur, 0, b, h, ti, s, li, lq, ucol, Qg, Kg, Vg, KT, QK, GC);
.LBB0_832:
	s_mov_b64 s[0:1], s[56:57]
	s_load_dwordx2 s[0:1], s[0:1], 0x108
	s_mov_b64 s[6:7], s[56:57]
	s_load_dwordx2 s[6:7], s[6:7], 0x108
	s_mov_b64 s[14:15], s[56:57]
	s_waitcnt lgkmcnt(0)
	s_add_u32 s18, s0, 0x4bb0000
	s_addc_u32 s19, s1, 0
	s_mov_b64 s[0:1], s[56:57]
	s_add_u32 s22, s6, 0x6c30000
	s_load_dwordx2 s[20:21], s[14:15], 0x108
	s_addc_u32 s23, s7, 0
	s_load_dwordx2 s[0:1], s[0:1], 0x108
	s_mov_b64 s[6:7], s[56:57]
	s_load_dwordx2 s[6:7], s[6:7], 0x108
	s_mov_b64 s[14:15], s[56:57]
	s_load_dwordx2 s[24:25], s[14:15], 0x108
	s_waitcnt lgkmcnt(0)
	s_add_u32 s28, s0, 0xad30000
	s_addc_u32 s29, s1, 0
	s_add_u32 s30, s6, 0xcdb0000
	s_addc_u32 s31, s7, 0
	s_add_u32 s39, s24, 0xef34000
	s_mov_b64 s[0:1], s[56:57]
	s_addc_u32 s42, s25, 0
	s_lshl_b32 s6, s36, 3
	s_ashr_i32 s7, s36, 5
	s_load_dwordx2 s[26:27], s[0:1], 0x108
	v_readfirstlane_b32 s0, v154
	s_bfe_u32 s1, s36, 0x20003
	s_and_b32 s6, s6, 56
	s_and_b32 s38, s7, 7
	s_add_i32 s6, s6, s7
	s_bfe_u32 s17, s0, 0x10006
	s_lshl_b32 s7, s38, 7
	s_lshl_b32 s37, s1, 5
	s_lshr_b32 s40, s0, 6
	s_ashr_i32 s34, s6, 3
	v_lshl_or_b32 v34, s17, 4, v156
	s_or_b32 s7, s7, s37
	s_lshr_b32 s0, s0, 3
	v_or_b32_e32 v4, s7, v34
	s_lshl_b32 s16, s34, 11
	s_and_b32 s7, s0, 0x1ffffff0
	s_add_i32 s0, s7, s16
	v_or_b32_e32 v76, s0, v70
	v_lshlrev_b32_e32 v68, 1, v4
	v_or_b32_e32 v6, 1, v76
	v_lshl_add_u64 v[4:5], s[20:21], 0, v[68:69]
	v_ashrrev_i32_e32 v77, 31, v76
	v_ashrrev_i32_e32 v7, 31, v6
	v_or_b32_e32 v0, s0, v156
	v_lshl_add_u64 v[74:75], v[4:5], 0, s[10:11]
	v_lshlrev_b64 v[4:5], 11, v[76:77]
	v_lshlrev_b64 v[8:9], 11, v[6:7]
	s_lshl_b32 s20, s34, 8
	s_mov_b64 s[14:15], s[56:57]
	v_ashrrev_i32_e32 v1, 31, v0
	v_lshl_add_u64 v[4:5], v[74:75], 0, v[4:5]
	v_lshl_add_u64 v[8:9], v[74:75], 0, v[8:9]
	s_or_b32 s34, s20, s38
	v_lshlrev_b64 v[0:1], 11, v[0:1]
	v_or_b32_e32 v4, 2, v76
	v_or_b32_e32 v32, 3, v76
	s_ashr_i32 s35, s34, 31
	v_lshl_add_u64 v[2:3], s[22:23], 0, v[0:1]
	s_lshl_b32 s8, s38, 8
	v_lshl_add_u64 v[0:1], s[18:19], 0, v[0:1]
	v_ashrrev_i32_e32 v5, 31, v4
	v_ashrrev_i32_e32 v33, 31, v32
	s_lshl_b64 s[20:21], s[34:35], 6
	v_lshl_add_u64 v[0:1], v[0:1], 0, s[8:9]
	v_lshlrev_b64 v[8:9], 11, v[4:5]
	v_lshlrev_b64 v[10:11], 11, v[32:33]
	s_add_u32 s20, s20, s7
	v_lshl_add_u64 v[2:3], v[2:3], 0, s[8:9]
	v_lshl_add_u64 v[0:1], v[0:1], 0, v[72:73]
	v_lshl_add_u64 v[8:9], v[74:75], 0, v[8:9]
	v_lshl_add_u64 v[10:11], v[74:75], 0, v[10:11]
	s_addc_u32 s21, s21, 0
	v_lshl_add_u64 v[2:3], v[2:3], 0, v[72:73]
	v_mov_b32_e32 v1, s21
	v_or_b32_e32 v0, s20, v156
	s_lshl_b64 s[20:21], s[34:35], 7
	s_lshl_b32 s35, s40, 4
	s_add_u32 s20, s20, s35
	s_addc_u32 s21, s21, 0
	v_lshlrev_b64 v[0:1], 7, v[0:1]
	v_mov_b32_e32 v3, s21
	v_or_b32_e32 v2, s20, v156
	v_lshl_add_u64 v[0:1], s[30:31], 0, v[0:1]
	v_lshlrev_b64 v[2:3], 7, v[2:3]
	s_lshl_b32 s43, s38, 2
	v_lshl_add_u64 v[0:1], v[0:1], 0, v[72:73]
	v_lshl_add_u64 v[2:3], s[28:29], 0, v[2:3]
	s_add_u32 s20, s39, s43
	v_lshl_add_u64 v[2:3], v[2:3], 0, v[72:73]
	s_addc_u32 s21, s42, 0
	v_lshlrev_b64 v[0:1], 5, v[76:77]
	v_lshl_add_u64 v[0:1], s[20:21], 0, v[0:1]
	v_lshlrev_b64 v[0:1], 5, v[6:7]
	v_lshl_add_u64 v[0:1], s[20:21], 0, v[0:1]
	v_lshlrev_b64 v[0:1], 5, v[4:5]
	s_or_b32 s40, s16, 63
	v_lshl_add_u64 v[0:1], s[20:21], 0, v[0:1]
	s_ashr_i32 s41, s40, 31
	v_lshlrev_b64 v[0:1], 5, v[32:33]
	s_lshl_b64 s[40:41], s[40:41], 5
	v_lshl_add_u64 v[0:1], s[20:21], 0, v[0:1]
	s_add_u32 s40, s39, s40
	s_addc_u32 s41, s42, s41
	v_mov_b32_e32 v2, s43
	s_add_u32 s22, s22, s8
	s_addc_u32 s23, s23, 0
	v_mul_u32_u24_e32 v32, 0x48, v34
	s_add_u32 s18, s18, s8
	v_lshlrev_b32_e32 v32, 1, v32
	s_addc_u32 s19, s19, 0
	s_lshl_b32 s8, s7, 1
	v_add_u32_e32 v106, 0, v32
	v_add3_u32 v101, v106, s8, v98
	v_add3_u32 v100, v92, s8, v32
	s_lshl_b32 s8, s38, 5
	s_waitcnt lgkmcnt(0)
	s_add_u32 s8, s26, s8
	v_lshl_add_u64 v[80:81], s[18:19], 0, v[72:73]
	s_addc_u32 s18, s27, 0
	s_lshl_b32 s1, s1, 3
	s_add_u32 s1, s8, s1
	s_addc_u32 s8, s18, 0
	s_lshl_b32 s17, s17, 2
	s_add_u32 s1, s1, s17
	s_addc_u32 s8, s8, 0
	s_add_u32 s18, s1, 0xefb6000
	s_addc_u32 s19, s8, 0
	s_ashr_i32 s17, s16, 31
	s_lshl_b64 s[26:27], s[16:17], 5
	s_load_dwordx2 s[14:15], s[14:15], 0x100
	v_lshl_add_u64 v[78:79], s[22:23], 0, v[72:73]
	s_or_b32 s22, s34, 8
	s_or_b32 s1, s26, s43
	v_or_b32_e32 v0, s7, v156
	v_mov_b32_e32 v1, v71
	s_add_u32 s1, s24, s1
	v_lshl_add_u64 v[2:3], s[30:31], 0, v[72:73]
	v_or_b32_e32 v4, s35, v156
	v_mov_b32_e32 v5, v71
	v_lshlrev_b64 v[0:1], 7, v[0:1]
	s_addc_u32 s8, s25, s27
	v_lshl_add_u64 v[6:7], s[28:29], 0, v[72:73]
	v_lshl_add_u64 v[82:83], v[2:3], 0, v[0:1]
	v_lshlrev_b64 v[0:1], 7, v[4:5]
	s_add_u32 s24, s1, 0xef34fe0
	v_mul_u32_u24_e32 v105, 0x110, v34
	v_lshl_add_u64 v[84:85], v[6:7], 0, v[0:1]
	s_addc_u32 s25, s8, 0
	v_add_u32_e32 v107, s0, v97
	s_mov_b32 s8, 0
	s_mov_b32 s17, 0
	v_mov_b32_e32 v4, 0
	v_mov_b32_e32 v5, v69
	v_mov_b32_e32 v6, v69
	v_mov_b32_e32 v7, v69
	v_mov_b32_e32 v0, 0
	v_mov_b32_e32 v1, v69
	v_mov_b32_e32 v2, v69
	v_mov_b32_e32 v3, v69
	s_and_b32 s0, s36, 7
	s_bfe_u32 s1, s36, 0x30005
	s_bfe_u32 s22, s36, 0x20003
	s_lshl_b32 s38, s0, 22
	s_lshl_b32 s39, s1, 8
	s_add_u32 s38, s38, s39
	s_add_u32 s24, s86, 0x6c30000
	s_addc_u32 s25, s87, 0
	s_add_u32 s24, s24, s38
	s_addc_u32 s25, s25, 0
	s_add_u32 s26, s86, 0x4bb0000
	s_addc_u32 s27, s87, 0
	s_add_u32 s26, s26, s38
	s_addc_u32 s27, s27, 0
	s_lshl_b32 s39, s22, 6
	s_add_u32 s98, s86, 0x8cb0000
	s_addc_u32 s99, s87, 0
	s_add_u32 s98, s98, s38
	s_addc_u32 s99, s99, 0
	s_add_u32 s98, s98, s39
	s_addc_u32 s99, s99, 0
	s_lshl_b32 s39, s0, 8
	s_add_u32 s39, s39, s1
	s_lshl_b32 s40, s39, 14
	s_add_u32 s28, s86, 0xad30000
; #define LAS __attribute__((address_space(3)))
; __device__ __forceinline__ float bf2f(unsigned short b) { return __uint_as_float((unsigned)b << 16); }
; __device__ __forceinline__ void scan_load(ScanFrag& f, int n, int b, int h, int ti, int s, int li, int lq, int ucol, const bf16* Qg, const bf16* Kg, const bf16* Vg, const bf16* KT, const bf16* QK, const float* GC) {
;     const int gcid = b * 32 + n, m0 = b * 2048 + n * 64;
;     const bf16* wrow = Kg + (size_t)(m0 + 16 * ti + li) * D + h * 128 + 8 * lq; const bf16* qrow = Qg + (size_t)(m0 + 16 * ti + li) * D + h * 128 + 8 * lq;
; #pragma unroll
;     for (int ks = 0; ks < 4; ++ks) { f.wA[ks] = *(const bf16x8*)(wrow + 32 * ks); f.qA[ks] = *(const bf16x8*)(qrow + 32 * ks); }
;     const bf16* qkrow = QK + ((size_t)(gcid * 8 + h) * 64 + 16 * ti + li) * 64 + 8 * lq; const bf16* ktrow = KT + ((size_t)(gcid * 8 + h) * 128 + 16 * s + li) * 64 + 8 * lq;
; #pragma unroll
;     for (int k2 = 0; k2 < 2; ++k2) { f.qkA[k2] = *(const bf16x8*)(qkrow + 32 * k2); f.kA[k2] = *(const bf16x8*)(ktrow + 32 * k2); }
;     const int rowb = m0 + 16 * ti + 4 * lq;
; #pragma unroll
;     for (int r = 0; r < 4; ++r) { f.uval[r] = bf2f(Vg[(size_t)(rowb + r) * D + ucol]); f.gcr[r] = GC[(size_t)(rowb + r) * 8 + h]; }
;     f.gl = GC[(size_t)(m0 + 63) * 8 + h];
; }
; __device__ __forceinline__ void scan_unit(LAS unsigned char* lds, int uidx, const bf16* Qg, const bf16* Kg, bf16* Vg, const bf16* KT, const bf16* QK, const float* GC, float* SSQ, float* sp_gdn) {
;     const int tid = threadIdx.x, lane = tid & 63, s = __builtin_amdgcn_readfirstlane(tid >> 6);
;     const int xc = uidx & 7, yy = uidx >> 3, slab = yy & 3, bh = xc * 8 + (yy >> 2), b = bh >> 3, h = bh & 7;
;     LAS bf16* St = (LAS bf16*)lds; LAS bf16* Vt = St + 2 * 32 * 136; LAS bf16* Vts = Vt + 32 * 72;
;     const int ti = s >> 1, c = s & 1, li = lane & 15, lq = lane >> 4;
;     f32x4 S0 = (f32x4){0.f, 0.f, 0.f, 0.f}, S1 = S0;
;     const int ucol = h * 128 + slab * 32 + 16 * c + li;
;     ScanFrag cur, nxt;
;     scan_load(cur, 0, b, h, ti, s, li, lq, ucol, Qg, Kg, Vg, KT, QK, GC);
	s_addc_u32 s29, s87, 0
	s_add_u32 s28, s28, s40
	s_addc_u32 s29, s29, 0
	s_lshl_b32 s40, s39, 13
	s_add_u32 s30, s86, 0xcdb0000
	s_addc_u32 s31, s87, 0
	s_add_u32 s30, s30, s40
	s_addc_u32 s31, s31, 0
	s_lshl_b32 s40, s0, 16
	s_lshl_b32 s41, s1, 2
	s_add_u32 s40, s40, s41
	s_add_u32 s100, s86, 0xef34000
	s_addc_u32 s101, s87, 0
	s_add_u32 s100, s100, s40
	s_addc_u32 s101, s101, 0
	v_lshrrev_b32_e32 v176, 4, v154
	v_and_b32_e32 v177, 15, v154
	v_lshlrev_b32_e32 v177, 4, v177
	v_lshl_add_u32 v41, v176, 11, v177
	v_add_u32_e32 v42, 0x10000, v41
	v_mul_u32_u24_e32 v47, 0x110, v176
	v_add_u32_e32 v47, v47, v177
	v_add_u32_e32 v47, 0x6800, v47
	v_lshlrev_b32_e32 v43, 4, v154
	v_add_u32_e32 v44, 0x2000, v43
	v_lshrrev_b32_e32 v176, 3, v154
	v_and_b32_e32 v177, 7, v154
	v_lshlrev_b32_e32 v177, 4, v177
	v_mul_u32_u24_e32 v48, 0x90, v176
	v_add_u32_e32 v48, v48, v177
	v_add_u32_e32 v48, 0xf000, v48
	v_add_u32_e32 v47, 0x4800, v48
	v_and_b32_e32 v176, 0x7f, v154
	v_lshrrev_b32_e32 v177, 7, v154
	v_lshlrev_b32_e32 v177, 4, v177
	v_mul_u32_u24_e32 v48, 0x90, v176
	v_add_u32_e32 v48, v48, v177
	v_add_u32_e32 v48, 0xf000, v48
	v_bfe_u32 v176, v154, 2, 6
	v_and_b32_e32 v177, 3, v154
	v_lshlrev_b32_e32 v177, 4, v177
	v_lshl_add_u32 v45, v176, 11, v177
	v_mul_u32_u24_e32 v49, 0x50, v176
	v_add_u32_e32 v49, v49, v177
	v_add_u32_e32 v49, 0x15c00, v49
	v_and_b32_e32 v176, 63, v154
	v_lshlrev_b32_e32 v46, 5, v176
	v_lshlrev_b32_e32 v50, 2, v176
	v_add_u32_e32 v50, 0x17000, v50
	v_lshrrev_b32_e32 v176, 7, v154
	v_and_b32_e32 v177, 15, v154
	v_lshl_add_u32 v176, v176, 4, v177
	v_bfe_u32 v178, v154, 4, 2
	v_lshlrev_b32_e32 v179, 4, v178
	v_mul_u32_u24_e32 v51, 0x110, v176
	v_add_u32_e32 v51, v51, v179
	v_add_u32_e32 v51, 0x6800, v51
	v_mul_u32_u24_e32 v52, 0x90, v176
	v_add_u32_e32 v52, v52, v179
	v_add_u32_e32 v52, 0x13800, v52
	v_lshrrev_b32_e32 v180, 6, v154
	v_lshl_add_u32 v180, v180, 4, v177
	v_mul_u32_u24_e32 v53, 0x90, v180
	v_add_u32_e32 v53, v53, v179
	v_add_u32_e32 v53, 0xf000, v53
	v_lshrrev_b32_e32 v180, 7, v154
	v_lshlrev_b32_e32 v180, 4, v180
	v_lshl_add_u32 v180, v178, 2, v180
	v_mul_u32_u24_e32 v54, 0x50, v180
	v_bfe_u32 v181, v154, 6, 1
	v_lshl_add_u32 v181, v181, 4, v177
	v_lshl_add_u32 v54, v181, 1, v54
	v_add_u32_e32 v54, 0x15c00, v54
	v_lshlrev_b32_e32 v55, 2, v180
	v_add_u32_e32 v55, 0x17000, v55
	v_mov_b32_e32 v174, 0x170fc
	v_lshrrev_b32_e32 v176, 7, v154
	v_bfe_u32 v178, v154, 4, 2
	v_lshl_add_u32 v176, v176, 4, v178
	v_and_b32_e32 v177, 15, v154
	v_lshlrev_b32_e32 v177, 4, v177
	v_lshl_add_u32 v236, v176, 11, v177
	v_add_u32_e32 v237, 0x2000, v236
	v_add_u32_e32 v238, 0x4000, v236
	v_add_u32_e32 v239, 0x6000, v236
	global_load_dwordx4 v[8:11], v236, s[24:25]
	global_load_dwordx4 v[12:15], v237, s[24:25]
	global_load_dwordx4 v[16:19], v238, s[24:25]
	global_load_dwordx4 v[20:23], v239, s[24:25]
	global_load_dwordx4 v[130:133], v236, s[26:27]
	global_load_dwordx4 v[134:137], v237, s[26:27]
	global_load_dwordx4 v[138:141], v238, s[26:27]
	global_load_dwordx4 v[142:145], v239, s[26:27]
	s_add_u32 s24, s24, 0x20000
	s_addc_u32 s25, s25, 0
	s_add_u32 s26, s26, 0x20000
	s_addc_u32 s27, s27, 0
	global_load_dwordx4 v[24:27], v43, s[28:29]
	global_load_dwordx4 v[28:31], v44, s[28:29]
	global_load_dwordx4 v[32:35], v43, s[30:31]
	global_load_dwordx4 v[36:39], v45, s[98:99]
	global_load_dword v40, v46, s[100:101]
	s_waitcnt vmcnt(0)
	ds_write_b128 v48, v[24:27]
	ds_write_b128 v48, v[28:31] offset:64
	ds_write_b128 v47, v[32:35]
	ds_write_b128 v49, v[36:39]
	ds_write_b32 v50, v40
	s_add_u32 s28, s28, 0x20000
	s_addc_u32 s29, s29, 0
	s_add_u32 s30, s30, 0x10000
	s_addc_u32 s31, s31, 0
	s_add_u32 s98, s98, 0x20000
	s_addc_u32 s99, s99, 0
	s_add_u32 s100, s100, 0x800
	s_addc_u32 s101, s101, 0
	global_load_dwordx4 v[24:27], v43, s[28:29]
	global_load_dwordx4 v[28:31], v44, s[28:29]
	global_load_dwordx4 v[32:35], v43, s[30:31]
	global_load_dwordx4 v[36:39], v45, s[98:99]
	global_load_dword v40, v46, s[100:101]
	s_add_u32 s28, s28, 0x20000
	s_addc_u32 s29, s29, 0
	s_add_u32 s30, s30, 0x10000
	s_addc_u32 s31, s31, 0
	s_add_u32 s98, s98, 0x20000
	s_addc_u32 s99, s99, 0
	s_add_u32 s100, s100, 0x800
	s_addc_u32 s101, s101, 0
	global_load_dwordx4 v[200:203], v43, s[28:29]
	global_load_dwordx4 v[204:207], v44, s[28:29]
	global_load_dwordx4 v[208:211], v43, s[30:31]
	global_load_dwordx4 v[212:215], v45, s[98:99]
	global_load_dword v216, v46, s[100:101]
; #define LAS __attribute__((address_space(3)))
; __device__ __forceinline__ void scan_unit(LAS unsigned char* lds, int uidx, const bf16* Qg, const bf16* Kg, bf16* Vg, const bf16* KT, const bf16* QK, const float* GC, float* SSQ, float* sp_gdn) {
;     ...
;         const int m0 = b * 2048 + n * 64, rowb = m0 + 16 * ti + 4 * lq;
;         __builtin_amdgcn_sched_barrier(0);
;         if (n + 1 < 32) scan_load(nxt, n + 1, b, h, ti, s, li, lq, ucol, Qg, Kg, Vg, KT, QK, GC);
;         __builtin_amdgcn_sched_barrier(0);
;         const bf16x8 (&wA)[4] = cur.wA; const bf16x8 (&qA)[4] = cur.qA; const bf16x8 (&qkA)[2] = cur.qkA; const bf16x8 (&kA)[2] = cur.kA;
;         const float (&uval)[4] = cur.uval; const float (&gcr)[4] = cur.gcr; const float gl = cur.gl;
;         LAS bf16* Sb = St + (n & 1) * 32 * 136;
;         { u32x2 w; w.x = cvt_pk_bf16(S0[0], S0[1]); w.y = cvt_pk_bf16(S0[2], S0[3]); *(LAS u32x2*)(Sb + li * 136 + 16 * s + 4 * lq) = w;
;           w.x = cvt_pk_bf16(S1[0], S1[1]); w.y = cvt_pk_bf16(S1[2], S1[3]); *(LAS u32x2*)(Sb + (16 + li) * 136 + 16 * s + 4 * lq) = w; }
;         LDS_BARRIER();
;         bf16x8 bS[4]; f32x4 acc = (f32x4){0.f, 0.f, 0.f, 0.f};
; #pragma unroll
;         for (int ks = 0; ks < 4; ++ks) { bS[ks] = *(const LAS bf16x8*)(Sb + (16 * c + li) * 136 + 32 * ks + 8 * lq); acc = __builtin_amdgcn_mfma_f32_16x16x32_bf16(wA[ks], bS[ks], acc, 0, 0, 0); }
;         f32x4 o = (f32x4){0.f, 0.f, 0.f, 0.f};
; #pragma unroll
;         for (int ks = 0; ks < 4; ++ks) o = __builtin_amdgcn_mfma_f32_16x16x32_bf16(qA[ks], bS[ks], o, 0, 0, 0);
;         { float vn[4], vs[4];
; #pragma unroll
;           for (int r = 0; r < 4; ++r) { vn[r] = uval[r] - acc[r]; vs[r] = vn[r] * __expf(gl - gcr[r]); }
;           u32x2 w; w.x = cvt_pk_bf16(vn[0], vn[1]); w.y = cvt_pk_bf16(vn[2], vn[3]); *(LAS u32x2*)(Vt + (16 * c + li) * 72 + 16 * ti + 4 * lq) = w;
;           w.x = cvt_pk_bf16(vs[0], vs[1]); w.y = cvt_pk_bf16(vs[2], vs[3]); *(LAS u32x2*)(Vts + (16 * c + li) * 72 + 16 * ti + 4 * lq) = w; }
;         LDS_BARRIER();
; #pragma unroll
;         for (int r = 0; r < 4; ++r) o[r] *= __expf(gcr[r]);
; #pragma unroll
;         for (int k2 = 0; k2 < 2; ++k2) { const bf16x8 bV = *(const LAS bf16x8*)(Vt + (16 * c + li) * 72 + 32 * k2 + 8 * lq); o = __builtin_amdgcn_mfma_f32_16x16x32_bf16(qkA[k2], bV, o, 0, 0, 0); }
; #pragma unroll
.LBB0_833:
	v_add_u32_e32 v86, s8, v76
	global_load_dwordx4 v[184:187], v236, s[24:25]
	global_load_dwordx4 v[188:191], v237, s[24:25]
	global_load_dwordx4 v[192:195], v238, s[24:25]
	global_load_dwordx4 v[196:199], v239, s[24:25]
	global_load_dwordx4 v[220:223], v236, s[26:27]
	global_load_dwordx4 v[224:227], v237, s[26:27]
	global_load_dwordx4 v[228:231], v238, s[26:27]
	global_load_dwordx4 v[232:235], v239, s[26:27]
	s_add_u32 s24, s24, 0x20000
	s_addc_u32 s25, s25, 0
	s_add_u32 s26, s26, 0x20000
	s_addc_u32 s27, s27, 0
	s_and_b32 s0, s17, 32
	s_mulk_i32 s0, 0x110
	s_add_i32 s0, s0, 0
	s_lshl_b32 s23, s35, 1
	s_add_i32 s1, s23, s0
	v_cvt_pk_bf16_f32 v88, v4, v5
	v_cvt_pk_bf16_f32 v89, v6, v7
	v_add3_u32 v150, s1, v90, v98
	ds_write_b64 v150, v[88:89]
	v_cvt_pk_bf16_f32 v88, v0, v1
	v_cvt_pk_bf16_f32 v89, v2, v3
	v_add3_u32 v150, s1, v91, v98
	ds_write_b64 v150, v[88:89]
	s_waitcnt lgkmcnt(0)
	s_barrier
	v_add3_u32 v88, s0, v105, v94
	ds_read_b128 v[162:165], v88
	ds_read_b128 v[166:169], v88 offset:64
	ds_read_b128 v[176:179], v55
	ds_read_b32 v108, v174
	ds_read_u16 v180, v54
	ds_read_u16 v181, v54 offset:80
	ds_read_u16 v182, v54 offset:160
	ds_read_u16 v183, v54 offset:240
	s_waitcnt lgkmcnt(0)
	s_cmpk_gt_u32 s8, 0x740
	s_cbranch_scc1 .LscanA_fw
	s_waitcnt vmcnt(21)
	s_branch .LscanA_fg
.LscanA_fw:
	s_waitcnt vmcnt(16)
.LscanA_fg:
	v_mov_b32_e32 v87, v176
	v_mov_b32_e32 v110, v177
	v_mov_b32_e32 v153, v178
	v_mov_b32_e32 v155, v179
	v_lshlrev_b32_e32 v66, 16, v180
	v_lshlrev_b32_e32 v67, 16, v181
	v_lshlrev_b32_e32 v64, 16, v182
	v_lshlrev_b32_e32 v65, 16, v183
	v_mfma_f32_16x16x32_bf16 v[114:117], v[8:11], v[162:165], 0
	v_sub_f32_e32 v89, v108, v110
	v_mul_f32_e32 v89, 0x3fb8aa3b, v89
	v_exp_f32_e32 v89, v89
	v_mfma_f32_16x16x32_bf16 v[114:117], v[12:15], v[166:169], v[114:117]
	ds_read_b128 v[118:121], v88 offset:128
	ds_read_b128 v[170:173], v88 offset:192
	ds_read_b128 v[146:149], v52
	ds_read_b128 v[158:161], v52 offset:64
	ds_read_b128 v[60:63], v53
	ds_read_b128 v[56:59], v53 offset:64
	v_sub_f32_e32 v88, v108, v87
	v_mul_f32_e32 v88, 0x3fb8aa3b, v88
	s_waitcnt lgkmcnt(5)
	v_mfma_f32_16x16x32_bf16 v[114:117], v[16:19], v[118:121], v[114:117]
	v_exp_f32_e32 v88, v88
	s_waitcnt lgkmcnt(4)
	v_mfma_f32_16x16x32_bf16 v[122:125], v[130:133], v[162:165], 0
	v_mfma_f32_16x16x32_bf16 v[114:117], v[20:23], v[170:173], v[114:117]
	v_sub_f32_e32 v126, v108, v153
	v_sub_f32_e32 v127, v108, v155
	v_mul_f32_e32 v126, 0x3fb8aa3b, v126
	v_mul_f32_e32 v127, 0x3fb8aa3b, v127
	v_exp_f32_e32 v126, v126
	v_exp_f32_e32 v127, v127
	v_mfma_f32_16x16x32_bf16 v[122:125], v[134:137], v[166:169], v[122:125]
	s_nop 0
	v_add_f32_e64 v66, v66, -v114
	v_add_f32_e64 v67, v67, -v115
	v_pk_add_f32 v[64:65], v[64:65], v[116:117] neg_lo:[0,1] neg_hi:[0,1]
	v_pk_mul_f32 v[88:89], v[88:89], v[66:67]
	v_pk_mul_f32 v[114:115], v[126:127], v[64:65]
	v_mfma_f32_16x16x32_bf16 v[118:121], v[138:141], v[118:121], v[122:125]
	v_cvt_pk_bf16_f32 v66, v66, v67
	v_cvt_pk_bf16_f32 v88, v88, v89
	v_cvt_pk_bf16_f32 v67, v64, v65
	v_cvt_pk_bf16_f32 v89, v114, v115
	v_mul_f32_e32 v64, 0x3fb8aa3b, v87
	ds_write_b64 v100, v[88:89] offset:22016
	v_exp_f32_e32 v88, v64
	v_mul_f32_e32 v64, 0x3fb8aa3b, v110
	ds_write_b64 v101, v[66:67] offset:17408
	v_exp_f32_e32 v89, v64
	v_mul_f32_e32 v64, 0x3fb8aa3b, v153
	s_waitcnt lgkmcnt(0)
	s_barrier
	v_exp_f32_e32 v122, v64
	v_mul_f32_e32 v64, 0x3fb8aa3b, v155
	v_add_u32_e32 v110, v106, v94
	v_exp_f32_e32 v123, v64
	ds_read_b128 v[64:67], v110 offset:17408
	v_mfma_f32_16x16x32_bf16 v[114:117], v[142:145], v[170:173], v[118:121]
	v_ashrrev_i32_e32 v87, 31, v86
	s_nop 1
	ds_read_b128 v[118:121], v110 offset:17472
	s_nop 3
	v_pk_mul_f32 v[114:115], v[88:89], v[114:115]
	v_pk_mul_f32 v[116:117], v[122:123], v[116:117]
	v_lshlrev_b64 v[88:89], 11, v[86:87]
	v_lshl_add_u64 v[88:89], v[74:75], 0, v[88:89]
	s_waitcnt lgkmcnt(1)
	v_mfma_f32_16x16x32_bf16 v[64:67], v[146:149], v[64:67], v[114:117]
	s_waitcnt lgkmcnt(0)
	v_mfma_f32_16x16x32_bf16 v[64:67], v[158:161], v[118:121], v[64:67]
	s_nop 7
	v_cvt_pk_bf16_f32 v114, v64, s0
	global_store_short v[88:89], v114, off
	v_mul_f32_e32 v88, v64, v64
	s_nop 1
	v_mov_b32_dpp v88, v88 row_ror:8 row_mask:0xf bank_mask:0xf bound_ctrl:1
	v_fmac_f32_e32 v88, v64, v64
	s_nop 1
	v_add_f32_dpp v64, v88, v88 row_ror:4 row_mask:0xf bank_mask:0xf bound_ctrl:1
	s_nop 1
	v_add_f32_dpp v64, v64, v64 row_ror:2 row_mask:0xf bank_mask:0xf bound_ctrl:1
	s_nop 1
	v_mov_b32_dpp v88, v64 row_ror:1 row_mask:0xf bank_mask:0xf bound_ctrl:1
	s_and_saveexec_b64 s[0:1], vcc
	s_cbranch_execz .LBB0_835
	v_add_f32_e32 v64, v64, v88
	v_lshlrev_b64 v[88:89], 8, v[86:87]
	v_lshl_add_u64 v[88:89], s[18:19], 0, v[88:89]
	global_store_dword v[88:89], v64, off

; #define LAS __attribute__((address_space(3)))
; __device__ __forceinline__ float bf2f(unsigned short b) { return __uint_as_float((unsigned)b << 16); }
; __device__ __forceinline__ void scan_load(ScanFrag& f, int n, int b, int h, int ti, int s, int li, int lq, int ucol, const bf16* Qg, const bf16* Kg, const bf16* Vg, const bf16* KT, const bf16* QK, const float* GC) {
;     const int gcid = b * 32 + n, m0 = b * 2048 + n * 64;
;     const bf16* wrow = Kg + (size_t)(m0 + 16 * ti + li) * D + h * 128 + 8 * lq; const bf16* qrow = Qg + (size_t)(m0 + 16 * ti + li) * D + h * 128 + 8 * lq;
; #pragma unroll
;     for (int ks = 0; ks < 4; ++ks) { f.wA[ks] = *(const bf16x8*)(wrow + 32 * ks); f.qA[ks] = *(const bf16x8*)(qrow + 32 * ks); }
;     const bf16* qkrow = QK + ((size_t)(gcid * 8 + h) * 64 + 16 * ti + li) * 64 + 8 * lq; const bf16* ktrow = KT + ((size_t)(gcid * 8 + h) * 128 + 16 * s + li) * 64 + 8 * lq;
; #pragma unroll
;     for (int k2 = 0; k2 < 2; ++k2) { f.qkA[k2] = *(const bf16x8*)(qkrow + 32 * k2); f.kA[k2] = *(const bf16x8*)(ktrow + 32 * k2); }
;     const int rowb = m0 + 16 * ti + 4 * lq;
; #pragma unroll
;     for (int r = 0; r < 4; ++r) { f.uval[r] = bf2f(Vg[(size_t)(rowb + r) * D + ucol]); f.gcr[r] = GC[(size_t)(rowb + r) * 8 + h]; }
;     f.gl = GC[(size_t)(m0 + 63) * 8 + h];
; __device__ __forceinline__ void scan_unit(LAS unsigned char* lds, int uidx, const bf16* Qg, const bf16* Kg, bf16* Vg, const bf16* KT, const bf16* QK, const float* GC, float* SSQ, float* sp_gdn) {
;     ...
;         const float eg = __expf(gl); S0 = S0 * eg; S1 = S1 * eg;
; #pragma unroll
;         for (int k2 = 0; k2 < 2; ++k2) { const bf16x8 b0 = *(const LAS bf16x8*)(Vts + li * 72 + 32 * k2 + 8 * lq), b1 = *(const LAS bf16x8*)(Vts + (16 + li) * 72 + 32 * k2 + 8 * lq);
;             S0 = __builtin_amdgcn_mfma_f32_16x16x32_bf16(kA[k2], b0, S0, 0, 0, 0); S1 = __builtin_amdgcn_mfma_f32_16x16x32_bf16(kA[k2], b1, S1, 0, 0, 0); }
;         __builtin_amdgcn_sched_barrier(0);
;         cur = nxt;
.LBB0_841:
	s_or_b64 exec, exec, s[0:1]
	v_mul_f32_e32 v64, 0x3fb8aa3b, v108
	v_exp_f32_e32 v108, v64
	ds_read_b128 v[64:67], v99 offset:22016
	ds_read_b128 v[86:89], v99 offset:24320
	ds_read_b128 v[114:117], v99 offset:22080
	ds_read_b128 v[118:121], v99 offset:24384
	v_pk_mul_f32 v[6:7], v[6:7], v[108:109] op_sel_hi:[1,0]
	v_pk_mul_f32 v[4:5], v[4:5], v[108:109] op_sel_hi:[1,0]
	v_pk_mul_f32 v[2:3], v[2:3], v[108:109] op_sel_hi:[1,0]
	v_pk_mul_f32 v[0:1], v[0:1], v[108:109] op_sel_hi:[1,0]
	s_waitcnt lgkmcnt(3)
	v_mfma_f32_16x16x32_bf16 v[4:7], v[60:63], v[64:67], v[4:7]
	s_waitcnt lgkmcnt(2)
	v_mfma_f32_16x16x32_bf16 v[0:3], v[60:63], v[86:89], v[0:3]
	s_waitcnt lgkmcnt(1)
	v_mfma_f32_16x16x32_bf16 v[4:7], v[56:59], v[114:117], v[4:7]
	s_waitcnt lgkmcnt(0)
	v_mfma_f32_16x16x32_bf16 v[0:3], v[56:59], v[118:121], v[0:3]
	s_cmpk_gt_u32 s8, 0x780
	s_cbranch_scc1 .LscanA_nostage
	s_cmpk_gt_u32 s8, 0x700
	s_cbranch_scc1 .LscanA_strict
	s_waitcnt vmcnt(21)
	s_branch .LscanA_wr
.LscanA_strict:
	s_waitcnt vmcnt(21)
.LscanA_wr:
	ds_write_b128 v48, v[24:27]
	ds_write_b128 v48, v[28:31] offset:64
	ds_write_b128 v47, v[32:35]
	ds_write_b128 v49, v[36:39]
	ds_write_b32 v50, v40
	s_cmpk_gt_u32 s8, 0x700
	s_cbranch_scc1 .LscanA_nostage
	s_add_u32 s28, s28, 0x20000
	s_addc_u32 s29, s29, 0
	s_add_u32 s30, s30, 0x10000
	s_addc_u32 s31, s31, 0
	s_add_u32 s98, s98, 0x20000
	s_addc_u32 s99, s99, 0
	s_add_u32 s100, s100, 0x800
	s_addc_u32 s101, s101, 0
	global_load_dwordx4 v[24:27], v43, s[28:29]
	global_load_dwordx4 v[28:31], v44, s[28:29]
	global_load_dwordx4 v[32:35], v43, s[30:31]
	global_load_dwordx4 v[36:39], v45, s[98:99]
	global_load_dword v40, v46, s[100:101]

; #define LAS __attribute__((address_space(3)))
; #define LDS_BARRIER() do { asm volatile("s_waitcnt lgkmcnt(0)" ::: "memory"); __builtin_amdgcn_s_barrier(); asm volatile("" ::: "memory"); } while (0)
; __device__ __forceinline__ void scan_unit(LAS unsigned char* lds, int uidx, const bf16* Qg, const bf16* Kg, bf16* Vg, const bf16* KT, const bf16* QK, const float* GC, float* SSQ, float* sp_gdn) {
;     ...
;         const int m0 = b * 2048 + n * 64, rowb = m0 + 16 * ti + 4 * lq;
;         __builtin_amdgcn_sched_barrier(0);
;         if (n + 1 < 32) scan_load(nxt, n + 1, b, h, ti, s, li, lq, ucol, Qg, Kg, Vg, KT, QK, GC);
;         __builtin_amdgcn_sched_barrier(0);
;         const bf16x8 (&wA)[4] = cur.wA; const bf16x8 (&qA)[4] = cur.qA; const bf16x8 (&qkA)[2] = cur.qkA; const bf16x8 (&kA)[2] = cur.kA;
;         const float (&uval)[4] = cur.uval; const float (&gcr)[4] = cur.gcr; const float gl = cur.gl;
;         LAS bf16* Sb = St + (n & 1) * 32 * 136;
;         { u32x2 w; w.x = cvt_pk_bf16(S0[0], S0[1]); w.y = cvt_pk_bf16(S0[2], S0[3]); *(LAS u32x2*)(Sb + li * 136 + 16 * s + 4 * lq) = w;
;           w.x = cvt_pk_bf16(S1[0], S1[1]); w.y = cvt_pk_bf16(S1[2], S1[3]); *(LAS u32x2*)(Sb + (16 + li) * 136 + 16 * s + 4 * lq) = w; }
;         LDS_BARRIER();
;         bf16x8 bS[4]; f32x4 acc = (f32x4){0.f, 0.f, 0.f, 0.f};
; #pragma unroll
;         for (int ks = 0; ks < 4; ++ks) { bS[ks] = *(const LAS bf16x8*)(Sb + (16 * c + li) * 136 + 32 * ks + 8 * lq); acc = __builtin_amdgcn_mfma_f32_16x16x32_bf16(wA[ks], bS[ks], acc, 0, 0, 0); }
.Lscan_bodyB:
	v_add_u32_e32 v86, s8, v76
	s_cmpk_gt_u32 s8, 0x780
	s_cbranch_scc1 .LscanB_nodir
	global_load_dwordx4 v[8:11], v236, s[24:25]
	global_load_dwordx4 v[12:15], v237, s[24:25]
	global_load_dwordx4 v[16:19], v238, s[24:25]
	global_load_dwordx4 v[20:23], v239, s[24:25]
	global_load_dwordx4 v[130:133], v236, s[26:27]
	global_load_dwordx4 v[134:137], v237, s[26:27]
	global_load_dwordx4 v[138:141], v238, s[26:27]
	global_load_dwordx4 v[142:145], v239, s[26:27]
	s_add_u32 s24, s24, 0x20000
	s_addc_u32 s25, s25, 0
	s_add_u32 s26, s26, 0x20000
	s_addc_u32 s27, s27, 0
.LscanB_nodir:
	s_and_b32 s0, s17, 32
	s_mulk_i32 s0, 0x110
	s_add_i32 s0, s0, 0
	s_lshl_b32 s23, s35, 1
	s_add_i32 s1, s23, s0
	v_cvt_pk_bf16_f32 v88, v4, v5
	v_cvt_pk_bf16_f32 v89, v6, v7
	v_add3_u32 v150, s1, v90, v98
	ds_write_b64 v150, v[88:89]
	v_cvt_pk_bf16_f32 v88, v0, v1
	v_cvt_pk_bf16_f32 v89, v2, v3
	v_add3_u32 v150, s1, v91, v98
	ds_write_b64 v150, v[88:89]
	s_waitcnt lgkmcnt(0)
	s_barrier
	v_add3_u32 v88, s0, v105, v94
	ds_read_b128 v[162:165], v88
	ds_read_b128 v[166:169], v88 offset:64
	ds_read_b128 v[176:179], v55
	ds_read_b32 v108, v174
	ds_read_u16 v180, v54
	ds_read_u16 v181, v54 offset:80
	ds_read_u16 v182, v54 offset:160
	ds_read_u16 v183, v54 offset:240
	s_waitcnt lgkmcnt(0)
	s_cmpk_gt_u32 s8, 0x780
	s_cbranch_scc1 .LscanB_fw
	s_waitcnt vmcnt(21)
	s_branch .LscanB_fg

; #define LAS __attribute__((address_space(3)))
; __device__ __forceinline__ unsigned short f2bf(float f) { return (unsigned short)(cvt_pk_bf16(f, 0.f) & 0xffffu); }
; #define LDS_BARRIER() do { asm volatile("s_waitcnt lgkmcnt(0)" ::: "memory"); __builtin_amdgcn_s_barrier(); asm volatile("" ::: "memory"); } while (0)
; __device__ __forceinline__ void scan_unit(LAS unsigned char* lds, int uidx, const bf16* Qg, const bf16* Kg, bf16* Vg, const bf16* KT, const bf16* QK, const float* GC, float* SSQ, float* sp_gdn) {
;     ...
;         bf16x8 bS[4]; f32x4 acc = (f32x4){0.f, 0.f, 0.f, 0.f};
; #pragma unroll
;         for (int ks = 0; ks < 4; ++ks) { bS[ks] = *(const LAS bf16x8*)(Sb + (16 * c + li) * 136 + 32 * ks + 8 * lq); acc = __builtin_amdgcn_mfma_f32_16x16x32_bf16(wA[ks], bS[ks], acc, 0, 0, 0); }
;         f32x4 o = (f32x4){0.f, 0.f, 0.f, 0.f};
; #pragma unroll
;         for (int ks = 0; ks < 4; ++ks) o = __builtin_amdgcn_mfma_f32_16x16x32_bf16(qA[ks], bS[ks], o, 0, 0, 0);
;         { float vn[4], vs[4];
; #pragma unroll
;           for (int r = 0; r < 4; ++r) { vn[r] = uval[r] - acc[r]; vs[r] = vn[r] * __expf(gl - gcr[r]); }
;           u32x2 w; w.x = cvt_pk_bf16(vn[0], vn[1]); w.y = cvt_pk_bf16(vn[2], vn[3]); *(LAS u32x2*)(Vt + (16 * c + li) * 72 + 16 * ti + 4 * lq) = w;
;           w.x = cvt_pk_bf16(vs[0], vs[1]); w.y = cvt_pk_bf16(vs[2], vs[3]); *(LAS u32x2*)(Vts + (16 * c + li) * 72 + 16 * ti + 4 * lq) = w; }
;         LDS_BARRIER();
; #pragma unroll
;         for (int r = 0; r < 4; ++r) o[r] *= __expf(gcr[r]);
; #pragma unroll
;         for (int k2 = 0; k2 < 2; ++k2) { const bf16x8 bV = *(const LAS bf16x8*)(Vt + (16 * c + li) * 72 + 32 * k2 + 8 * lq); o = __builtin_amdgcn_mfma_f32_16x16x32_bf16(qkA[k2], bV, o, 0, 0, 0); }
; #pragma unroll
;         for (int r = 0; r < 4; ++r) { Vg[(size_t)(rowb + r) * D + ucol] = f2bf(o[r]); const float sq = row16_sum(o[r] * o[r]);
;             if (li == 0) SSQ[((size_t)(rowb + r) * 8 + h) * 8 + slab * 2 + c] = sq; }
.LscanB_fg:
	v_mov_b32_e32 v87, v176
	v_mov_b32_e32 v110, v177
	v_mov_b32_e32 v153, v178
	v_mov_b32_e32 v155, v179
	v_lshlrev_b32_e32 v66, 16, v180
	v_lshlrev_b32_e32 v67, 16, v181
	v_lshlrev_b32_e32 v64, 16, v182
	v_lshlrev_b32_e32 v65, 16, v183
	v_mfma_f32_16x16x32_bf16 v[114:117], v[184:187], v[162:165], 0
	v_sub_f32_e32 v89, v108, v110
	v_mul_f32_e32 v89, 0x3fb8aa3b, v89
	v_exp_f32_e32 v89, v89
	v_mfma_f32_16x16x32_bf16 v[114:117], v[188:191], v[166:169], v[114:117]
	ds_read_b128 v[118:121], v88 offset:128
	ds_read_b128 v[170:173], v88 offset:192
	ds_read_b128 v[146:149], v52
	ds_read_b128 v[158:161], v52 offset:64
	ds_read_b128 v[60:63], v53
	ds_read_b128 v[56:59], v53 offset:64
	v_sub_f32_e32 v88, v108, v87
	v_mul_f32_e32 v88, 0x3fb8aa3b, v88
	s_waitcnt lgkmcnt(5)
	v_mfma_f32_16x16x32_bf16 v[114:117], v[192:195], v[118:121], v[114:117]
	v_exp_f32_e32 v88, v88
	s_waitcnt lgkmcnt(4)
	v_mfma_f32_16x16x32_bf16 v[122:125], v[220:223], v[162:165], 0
	v_mfma_f32_16x16x32_bf16 v[114:117], v[196:199], v[170:173], v[114:117]
	v_sub_f32_e32 v126, v108, v153
	v_sub_f32_e32 v127, v108, v155
	v_mul_f32_e32 v126, 0x3fb8aa3b, v126
	v_mul_f32_e32 v127, 0x3fb8aa3b, v127
	v_exp_f32_e32 v126, v126
	v_exp_f32_e32 v127, v127
	v_mfma_f32_16x16x32_bf16 v[122:125], v[224:227], v[166:169], v[122:125]
	s_nop 0
	v_add_f32_e64 v66, v66, -v114
	v_add_f32_e64 v67, v67, -v115
	v_pk_add_f32 v[64:65], v[64:65], v[116:117] neg_lo:[0,1] neg_hi:[0,1]
	v_pk_mul_f32 v[88:89], v[88:89], v[66:67]
	v_pk_mul_f32 v[114:115], v[126:127], v[64:65]
	v_mfma_f32_16x16x32_bf16 v[118:121], v[228:231], v[118:121], v[122:125]
	v_cvt_pk_bf16_f32 v66, v66, v67
	v_cvt_pk_bf16_f32 v88, v88, v89
	v_cvt_pk_bf16_f32 v67, v64, v65
	v_cvt_pk_bf16_f32 v89, v114, v115
	v_mul_f32_e32 v64, 0x3fb8aa3b, v87
	ds_write_b64 v100, v[88:89] offset:22016
	v_exp_f32_e32 v88, v64
	v_mul_f32_e32 v64, 0x3fb8aa3b, v110
	ds_write_b64 v101, v[66:67] offset:17408
	v_exp_f32_e32 v89, v64
	v_mul_f32_e32 v64, 0x3fb8aa3b, v153
	s_waitcnt lgkmcnt(0)
	s_barrier
	v_exp_f32_e32 v122, v64
	v_mul_f32_e32 v64, 0x3fb8aa3b, v155
	v_add_u32_e32 v110, v106, v94
	v_exp_f32_e32 v123, v64
	ds_read_b128 v[64:67], v110 offset:17408
	v_mfma_f32_16x16x32_bf16 v[114:117], v[232:235], v[170:173], v[118:121]
	v_ashrrev_i32_e32 v87, 31, v86
	s_nop 1
	ds_read_b128 v[118:121], v110 offset:17472
	s_nop 3
	v_pk_mul_f32 v[114:115], v[88:89], v[114:115]
	v_pk_mul_f32 v[116:117], v[122:123], v[116:117]
	v_lshlrev_b64 v[88:89], 11, v[86:87]
	v_lshl_add_u64 v[88:89], v[74:75], 0, v[88:89]
	s_waitcnt lgkmcnt(1)
	v_mfma_f32_16x16x32_bf16 v[64:67], v[146:149], v[64:67], v[114:117]
	s_waitcnt lgkmcnt(0)
	v_mfma_f32_16x16x32_bf16 v[64:67], v[158:161], v[118:121], v[64:67]
	s_nop 7
	v_cvt_pk_bf16_f32 v114, v64, s0
	global_store_short v[88:89], v114, off
	v_mul_f32_e32 v88, v64, v64
	s_nop 1
	v_mov_b32_dpp v88, v88 row_ror:8 row_mask:0xf bank_mask:0xf bound_ctrl:1
	v_fmac_f32_e32 v88, v64, v64
	s_nop 1
	v_add_f32_dpp v64, v88, v88 row_ror:4 row_mask:0xf bank_mask:0xf bound_ctrl:1
	s_nop 1
	v_add_f32_dpp v64, v64, v64 row_ror:2 row_mask:0xf bank_mask:0xf bound_ctrl:1
	s_nop 1
	v_mov_b32_dpp v88, v64 row_ror:1 row_mask:0xf bank_mask:0xf bound_ctrl:1
	s_and_saveexec_b64 s[0:1], vcc
	s_cbranch_execz .LscanB_835
	v_add_f32_e32 v64, v64, v88
	v_lshlrev_b64 v[88:89], 8, v[86:87]
	v_lshl_add_u64 v[88:89], s[18:19], 0, v[88:89]
	global_store_dword v[88:89], v64, off

; __device__ __forceinline__ float bf2f(unsigned short b) { return __uint_as_float((unsigned)b << 16); }
; __device__ __forceinline__ void scan_load(ScanFrag& f, int n, int b, int h, int ti, int s, int li, int lq, int ucol, const bf16* Qg, const bf16* Kg, const bf16* Vg, const bf16* KT, const bf16* QK, const float* GC) {
;     const int gcid = b * 32 + n, m0 = b * 2048 + n * 64;
;     const bf16* wrow = Kg + (size_t)(m0 + 16 * ti + li) * D + h * 128 + 8 * lq; const bf16* qrow = Qg + (size_t)(m0 + 16 * ti + li) * D + h * 128 + 8 * lq;
; #pragma unroll
;     for (int ks = 0; ks < 4; ++ks) { f.wA[ks] = *(const bf16x8*)(wrow + 32 * ks); f.qA[ks] = *(const bf16x8*)(qrow + 32 * ks); }
;     const bf16* qkrow = QK + ((size_t)(gcid * 8 + h) * 64 + 16 * ti + li) * 64 + 8 * lq; const bf16* ktrow = KT + ((size_t)(gcid * 8 + h) * 128 + 16 * s + li) * 64 + 8 * lq;
; #pragma unroll
;     for (int k2 = 0; k2 < 2; ++k2) { f.qkA[k2] = *(const bf16x8*)(qkrow + 32 * k2); f.kA[k2] = *(const bf16x8*)(ktrow + 32 * k2); }
;     const int rowb = m0 + 16 * ti + 4 * lq;
; #pragma unroll
;     for (int r = 0; r < 4; ++r) { f.uval[r] = bf2f(Vg[(size_t)(rowb + r) * D + ucol]); f.gcr[r] = GC[(size_t)(rowb + r) * 8 + h]; }
;     f.gl = GC[(size_t)(m0 + 63) * 8 + h];
.LscanB_wr:
	ds_write_b128 v48, v[200:203]
	ds_write_b128 v48, v[204:207] offset:64
	ds_write_b128 v47, v[208:211]
	ds_write_b128 v49, v[212:215]
	ds_write_b32 v50, v216
	s_cmpk_gt_u32 s8, 0x700
	s_cbranch_scc1 .LscanB_nostage
	s_add_u32 s28, s28, 0x20000
	s_addc_u32 s29, s29, 0
	s_add_u32 s30, s30, 0x10000
	s_addc_u32 s31, s31, 0
	s_add_u32 s98, s98, 0x20000
	s_addc_u32 s99, s99, 0
	s_add_u32 s100, s100, 0x800
	s_addc_u32 s101, s101, 0
	global_load_dwordx4 v[200:203], v43, s[28:29]
	global_load_dwordx4 v[204:207], v44, s[28:29]
	global_load_dwordx4 v[208:211], v43, s[30:31]
	global_load_dwordx4 v[212:215], v45, s[98:99]
	global_load_dword v216, v46, s[100:101]
